# stack: MLA top-of-tile adds + GEMM header vmcnt(0) removed + SwiGLU epilogue without the dead denormal arm of rsqrtf
# baseline (speedup 1.0000x reference)
; __device__ __forceinline__ float rstd_from(const float* ps, int row, int off4, int n4, float inv_dim, int fq) {
;     float s = 0.f;
;     if (fq < n4) { const f32x4 v = *((const f32x4*)(ps + (size_t)row * 16) + off4 + fq); s = (v[0] + v[1]) + (v[2] + v[3]); }
;     s += __shfl_xor(s, 16); s += __shfl_xor(s, 32);
;     return rsqrtf(s * inv_dim + 1e-6f);
;     __device__ __forceinline__ void operator()(const f32x4 (&acc)[2][2][4][2], const Unit& u, int wr, int wc, int fr, int fq) const {
;         const int row0 = u.pm * BM + wr * 64 + fr, col0 = u.pn * 128 + wc * 32 + 8 * fq;
; #pragma unroll
;         for (int ai = 0; ai < 2; ++ai)
; #pragma unroll
;             for (int m = 0; m < 4; ++m) {
;                 const int row = row0 + ai * HALF + m * 16;
;                 const float rs = rstd_from(ps, row, 0, 4, 1.f / 1024.f, fq);
;                 float hv[8];
; #pragma unroll
;                 for (int n = 0; n < 2; ++n)
; #pragma unroll
;                     for (int e = 0; e < 4; ++e) { const float gt = acc[ai][0][m][n][e] * rs, up = acc[ai][1][m][n][e] * rs;
;                         hv[n * 4 + e] = gt * __builtin_amdgcn_rcpf(1.f + __builtin_amdgcn_exp2f(-1.4426950408889634f * gt)) * up; }
.LBB0_1171:
	v_and_b32_e32 v143, 64, v204
	v_xor_b32_e32 v141, 16, v204
	v_add_u32_e32 v143, 64, v143
	v_cmp_lt_i32_e32 vcc, v141, v143
	v_lshl_add_u32 v140, s7, 8, v145
	v_lshl_or_b32 v142, s2, 7, v147
	v_cndmask_b32_e32 v141, v204, v141, vcc
	v_lshlrev_b32_e32 v149, 2, v141
	v_xor_b32_e32 v141, 32, v204
	v_cmp_lt_i32_e32 vcc, v141, v143
	v_ashrrev_i32_e32 v143, 31, v142
	s_movk_i32 s4, 0x2000
	v_cndmask_b32_e32 v141, v204, v141, vcc
	v_lshlrev_b32_e32 v150, 2, v141
	v_ashrrev_i32_e32 v141, 31, v140
	v_lshlrev_b64 v[152:153], 6, v[140:141]
	s_mov_b32 s5, 0
	v_lshl_add_u64 v[152:153], v[134:135], 0, v[152:153]
	v_lshl_add_u64 v[154:155], v[152:153], 0, s[4:5]
	global_load_dwordx4 v[156:159], v[152:153], off
	global_load_dwordx4 v[160:163], v[152:153], off offset:1024
	global_load_dwordx4 v[164:167], v[152:153], off offset:2048
	global_load_dwordx4 v[172:175], v[152:153], off offset:3072
	global_load_dwordx4 v[176:179], v[154:155], off
	global_load_dwordx4 v[180:183], v[154:155], off offset:1024
	global_load_dwordx4 v[184:187], v[154:155], off offset:2048
	global_load_dwordx4 v[188:191], v[154:155], off offset:3072
	v_mov_b64_e32 v[236:237], s[26:27]
	v_lshlrev_b64 v[238:239], 1, v[142:143]
	v_mad_i64_i32 v[234:235], s[4:5], v140, s17, v[236:237]
	s_lshl_b32 s4, s17, 4
	s_mov_b32 s5, 0
	v_lshl_add_u64 v[234:235], v[234:235], 0, v[238:239]
	v_lshl_add_u64 v[236:237], s[4:5], 0, v[234:235]
	v_lshl_add_u64 v[238:239], s[4:5], 1, v[234:235]
	v_lshl_add_u64 v[240:241], s[4:5], 1, v[236:237]
	s_waitcnt vmcnt(7)
	v_add_f32_e32 v156, v157, v156
	v_add_f32_e32 v158, v158, v159
	s_waitcnt vmcnt(6)
	v_add_f32_e32 v160, v161, v160
	v_add_f32_e32 v162, v162, v163
	s_waitcnt vmcnt(5)
	v_add_f32_e32 v164, v165, v164
	v_add_f32_e32 v166, v166, v167
	s_waitcnt vmcnt(4)
	v_add_f32_e32 v172, v173, v172
	v_add_f32_e32 v174, v174, v175
	s_waitcnt vmcnt(3)
	v_add_f32_e32 v176, v177, v176
	v_add_f32_e32 v178, v178, v179
	s_waitcnt vmcnt(2)
	v_add_f32_e32 v180, v181, v180
	v_add_f32_e32 v182, v182, v183
	s_waitcnt vmcnt(1)
	v_add_f32_e32 v184, v185, v184
	v_add_f32_e32 v186, v186, v187
	s_waitcnt vmcnt(0)
	v_add_f32_e32 v188, v189, v188
	v_add_f32_e32 v190, v190, v191
	v_add_f32_e32 v156, v156, v158
	v_add_f32_e32 v160, v160, v162
	v_add_f32_e32 v164, v164, v166
	v_add_f32_e32 v172, v172, v174
	v_add_f32_e32 v176, v176, v178
	v_add_f32_e32 v180, v180, v182
	v_add_f32_e32 v184, v184, v186
	v_add_f32_e32 v188, v188, v190
	ds_bpermute_b32 v157, v149, v156
	ds_bpermute_b32 v161, v149, v160
	ds_bpermute_b32 v165, v149, v164
	ds_bpermute_b32 v173, v149, v172
	ds_bpermute_b32 v177, v149, v176
	ds_bpermute_b32 v181, v149, v180
	ds_bpermute_b32 v185, v149, v184
	ds_bpermute_b32 v189, v149, v188
	s_waitcnt lgkmcnt(7)
	v_add_f32_e32 v156, v156, v157
	s_waitcnt lgkmcnt(6)
	v_add_f32_e32 v160, v160, v161
	s_waitcnt lgkmcnt(5)
	v_add_f32_e32 v164, v164, v165
	s_waitcnt lgkmcnt(4)
	v_add_f32_e32 v172, v172, v173
	s_waitcnt lgkmcnt(3)
	v_add_f32_e32 v176, v176, v177
	s_waitcnt lgkmcnt(2)
	v_add_f32_e32 v180, v180, v181
	s_waitcnt lgkmcnt(1)
	v_add_f32_e32 v184, v184, v185
	s_waitcnt lgkmcnt(0)
	v_add_f32_e32 v188, v188, v189
	ds_bpermute_b32 v157, v150, v156
	ds_bpermute_b32 v161, v150, v160
	ds_bpermute_b32 v165, v150, v164
	ds_bpermute_b32 v173, v150, v172
	ds_bpermute_b32 v177, v150, v176
	ds_bpermute_b32 v181, v150, v180
	ds_bpermute_b32 v185, v150, v184
	ds_bpermute_b32 v189, v150, v188
	s_waitcnt lgkmcnt(7)
	v_add_f32_e32 v156, v156, v157
	s_waitcnt lgkmcnt(6)
	v_add_f32_e32 v160, v160, v161
	s_waitcnt lgkmcnt(5)
	v_add_f32_e32 v164, v164, v165
	s_waitcnt lgkmcnt(4)
	v_add_f32_e32 v172, v172, v173
	s_waitcnt lgkmcnt(3)
	v_add_f32_e32 v176, v176, v177
	s_waitcnt lgkmcnt(2)
	v_add_f32_e32 v180, v180, v181
	s_waitcnt lgkmcnt(1)
	v_add_f32_e32 v184, v184, v185
	s_waitcnt lgkmcnt(0)
	v_add_f32_e32 v188, v188, v189
	v_fmamk_f32 v156, v156, 0x3a800000, v202
	v_fmamk_f32 v160, v160, 0x3a800000, v202
	v_fmamk_f32 v164, v164, 0x3a800000, v202
	v_fmamk_f32 v172, v172, 0x3a800000, v202
	v_fmamk_f32 v176, v176, 0x3a800000, v202
	v_fmamk_f32 v180, v180, 0x3a800000, v202
	v_fmamk_f32 v184, v184, 0x3a800000, v202
	v_fmamk_f32 v188, v188, 0x3a800000, v202
	v_rsq_f32_e32 v158, v156
	v_rsq_f32_e32 v162, v160
	v_rsq_f32_e32 v166, v164
	v_rsq_f32_e32 v174, v172
	v_rsq_f32_e32 v178, v176
	v_rsq_f32_e32 v182, v180
	v_rsq_f32_e32 v186, v184
	v_rsq_f32_e32 v190, v188
	s_lshl_b32 s4, s17, 4
	s_mov_b32 s5, 0
	v_mul_f32_e32 v120, v120, v158
	v_mul_f32_e32 v121, v121, v158
	v_mul_f32_e32 v122, v122, v158
	v_mul_f32_e32 v123, v123, v158
	v_mul_f32_e32 v112, v112, v158
	v_mul_f32_e32 v113, v113, v158
	v_mul_f32_e32 v114, v114, v158
	v_mul_f32_e32 v115, v115, v158
	v_mul_f32_e32 v218, 0xbfb8aa3b, v120
	v_mul_f32_e32 v219, 0xbfb8aa3b, v121
	v_mul_f32_e32 v220, 0xbfb8aa3b, v122
	v_mul_f32_e32 v221, 0xbfb8aa3b, v123
	v_mul_f32_e32 v222, 0xbfb8aa3b, v112
	v_mul_f32_e32 v223, 0xbfb8aa3b, v113
	v_mul_f32_e32 v224, 0xbfb8aa3b, v114
	v_mul_f32_e32 v225, 0xbfb8aa3b, v115
	v_exp_f32_e32 v218, v218
	v_exp_f32_e32 v219, v219
	v_exp_f32_e32 v220, v220
	v_exp_f32_e32 v221, v221
	v_exp_f32_e32 v222, v222
	v_exp_f32_e32 v223, v223
	v_exp_f32_e32 v224, v224
	v_exp_f32_e32 v225, v225
	v_add_f32_e32 v218, 1.0, v218
	v_add_f32_e32 v219, 1.0, v219
	v_add_f32_e32 v220, 1.0, v220
	v_add_f32_e32 v221, 1.0, v221
	v_add_f32_e32 v222, 1.0, v222
	v_add_f32_e32 v223, 1.0, v223
	v_add_f32_e32 v224, 1.0, v224
	v_add_f32_e32 v225, 1.0, v225
	v_rcp_f32_e32 v218, v218
	v_rcp_f32_e32 v219, v219
	v_rcp_f32_e32 v220, v220
	v_rcp_f32_e32 v221, v221
	v_rcp_f32_e32 v222, v222
	v_rcp_f32_e32 v223, v223
	v_rcp_f32_e32 v224, v224
; __device__ __forceinline__ unsigned cvt_pk_bf16(float lo, float hi) { unsigned r; asm volatile("v_cvt_pk_bf16_f32 %0, %1, %2" : "=v"(r) : "v"(lo), "v"(hi)); return r; }
;     __device__ __forceinline__ void operator()(const f32x4 (&acc)[2][2][4][2], const Unit& u, int wr, int wc, int fr, int fq) const {
;     ...
;                     for (int e = 0; e < 4; ++e) { const float gt = acc[ai][0][m][n][e] * rs, up = acc[ai][1][m][n][e] * rs;
;                         hv[n * 4 + e] = gt * __builtin_amdgcn_rcpf(1.f + __builtin_amdgcn_exp2f(-1.4426950408889634f * gt)) * up; }
;                 u32x4 w; w.x = cvt_pk_bf16(hv[0], hv[1]); w.y = cvt_pk_bf16(hv[2], hv[3]); w.z = cvt_pk_bf16(hv[4], hv[5]); w.w = cvt_pk_bf16(hv[6], hv[7]);
;                 *(u32x4*)(H + (size_t)row * 2816 + col0) = w;
	v_rcp_f32_e32 v225, v225
	v_mul_f32_e32 v218, v120, v218
	v_mul_f32_e32 v219, v121, v219
	v_mul_f32_e32 v220, v122, v220
	v_mul_f32_e32 v221, v123, v221
	v_mul_f32_e32 v222, v112, v222
	v_mul_f32_e32 v223, v113, v223
	v_mul_f32_e32 v224, v114, v224
	v_mul_f32_e32 v225, v115, v225
	v_mul_f32_e32 v124, v124, v158
	v_mul_f32_e32 v125, v125, v158
	v_mul_f32_e32 v126, v126, v158
	v_mul_f32_e32 v127, v127, v158
	v_mul_f32_e32 v116, v116, v158
	v_mul_f32_e32 v117, v117, v158
	v_mul_f32_e32 v118, v118, v158
	v_mul_f32_e32 v119, v119, v158
	v_mul_f32_e32 v124, v124, v218
	v_mul_f32_e32 v125, v125, v219
	v_mul_f32_e32 v126, v126, v220
	v_mul_f32_e32 v127, v127, v221
	v_mul_f32_e32 v116, v116, v222
	v_mul_f32_e32 v117, v117, v223
	v_mul_f32_e32 v118, v118, v224
	v_mul_f32_e32 v119, v119, v225
	v_cvt_pk_bf16_f32 v226, v124, v125
	v_cvt_pk_bf16_f32 v227, v126, v127
	v_cvt_pk_bf16_f32 v228, v116, v117
	v_cvt_pk_bf16_f32 v229, v118, v119
	global_store_dwordx4 v[234:235], v[226:229], off
	v_mul_f32_e32 v104, v104, v162
	v_mul_f32_e32 v105, v105, v162
	v_mul_f32_e32 v106, v106, v162
	v_mul_f32_e32 v107, v107, v162
	v_mul_f32_e32 v96, v96, v162
	v_mul_f32_e32 v97, v97, v162
	v_mul_f32_e32 v98, v98, v162
	v_mul_f32_e32 v99, v99, v162
	v_mul_f32_e32 v218, 0xbfb8aa3b, v104
	v_mul_f32_e32 v219, 0xbfb8aa3b, v105
	v_mul_f32_e32 v220, 0xbfb8aa3b, v106
	v_mul_f32_e32 v221, 0xbfb8aa3b, v107
	v_mul_f32_e32 v222, 0xbfb8aa3b, v96
	v_mul_f32_e32 v223, 0xbfb8aa3b, v97
	v_mul_f32_e32 v224, 0xbfb8aa3b, v98
	v_mul_f32_e32 v225, 0xbfb8aa3b, v99
	v_exp_f32_e32 v218, v218
	v_exp_f32_e32 v219, v219
	v_exp_f32_e32 v220, v220
	v_exp_f32_e32 v221, v221
	v_exp_f32_e32 v222, v222
	v_exp_f32_e32 v223, v223
	v_exp_f32_e32 v224, v224
	v_exp_f32_e32 v225, v225
	v_add_f32_e32 v218, 1.0, v218
	v_add_f32_e32 v219, 1.0, v219
	v_add_f32_e32 v220, 1.0, v220
	v_add_f32_e32 v221, 1.0, v221
	v_add_f32_e32 v222, 1.0, v222
	v_add_f32_e32 v223, 1.0, v223
	v_add_f32_e32 v224, 1.0, v224
	v_add_f32_e32 v225, 1.0, v225
	v_rcp_f32_e32 v218, v218
	v_rcp_f32_e32 v219, v219
	v_rcp_f32_e32 v220, v220
	v_rcp_f32_e32 v221, v221
	v_rcp_f32_e32 v222, v222
	v_rcp_f32_e32 v223, v223
	v_rcp_f32_e32 v224, v224
	v_rcp_f32_e32 v225, v225
	v_mul_f32_e32 v218, v104, v218
	v_mul_f32_e32 v219, v105, v219
	v_mul_f32_e32 v220, v106, v220
	v_mul_f32_e32 v221, v107, v221
	v_mul_f32_e32 v222, v96, v222
	v_mul_f32_e32 v223, v97, v223
	v_mul_f32_e32 v224, v98, v224
	v_mul_f32_e32 v225, v99, v225
	v_mul_f32_e32 v108, v108, v162
	v_mul_f32_e32 v109, v109, v162
	v_mul_f32_e32 v110, v110, v162
	v_mul_f32_e32 v111, v111, v162
	v_mul_f32_e32 v100, v100, v162
	v_mul_f32_e32 v101, v101, v162
	v_mul_f32_e32 v102, v102, v162
	v_mul_f32_e32 v103, v103, v162
	v_mul_f32_e32 v108, v108, v218
	v_mul_f32_e32 v109, v109, v219
	v_mul_f32_e32 v110, v110, v220
	v_mul_f32_e32 v111, v111, v221
	v_mul_f32_e32 v100, v100, v222
	v_mul_f32_e32 v101, v101, v223
	v_mul_f32_e32 v102, v102, v224
	v_mul_f32_e32 v103, v103, v225
	v_cvt_pk_bf16_f32 v230, v108, v109
	v_cvt_pk_bf16_f32 v231, v110, v111
	v_cvt_pk_bf16_f32 v232, v100, v101
	v_cvt_pk_bf16_f32 v233, v102, v103
	global_store_dwordx4 v[236:237], v[230:233], off
	v_mul_f32_e32 v88, v88, v166
	v_mul_f32_e32 v89, v89, v166
	v_mul_f32_e32 v90, v90, v166
	v_mul_f32_e32 v91, v91, v166
	v_mul_f32_e32 v80, v80, v166
	v_mul_f32_e32 v81, v81, v166
	v_mul_f32_e32 v82, v82, v166
	v_mul_f32_e32 v83, v83, v166
	v_mul_f32_e32 v218, 0xbfb8aa3b, v88
	v_mul_f32_e32 v219, 0xbfb8aa3b, v89
	v_mul_f32_e32 v220, 0xbfb8aa3b, v90
	v_mul_f32_e32 v221, 0xbfb8aa3b, v91
	v_mul_f32_e32 v222, 0xbfb8aa3b, v80
	v_mul_f32_e32 v223, 0xbfb8aa3b, v81
	v_mul_f32_e32 v224, 0xbfb8aa3b, v82
	v_mul_f32_e32 v225, 0xbfb8aa3b, v83
	v_exp_f32_e32 v218, v218
	v_exp_f32_e32 v219, v219
	v_exp_f32_e32 v220, v220
	v_exp_f32_e32 v221, v221
	v_exp_f32_e32 v222, v222
	v_exp_f32_e32 v223, v223
	v_exp_f32_e32 v224, v224
	v_exp_f32_e32 v225, v225
	v_add_f32_e32 v218, 1.0, v218
	v_add_f32_e32 v219, 1.0, v219
	v_add_f32_e32 v220, 1.0, v220
	v_add_f32_e32 v221, 1.0, v221
	v_add_f32_e32 v222, 1.0, v222
	v_add_f32_e32 v223, 1.0, v223
	v_add_f32_e32 v224, 1.0, v224
	v_add_f32_e32 v225, 1.0, v225
	v_rcp_f32_e32 v218, v218
	v_rcp_f32_e32 v219, v219
	v_rcp_f32_e32 v220, v220
	v_rcp_f32_e32 v221, v221
	v_rcp_f32_e32 v222, v222
	v_rcp_f32_e32 v223, v223
	v_rcp_f32_e32 v224, v224
	v_rcp_f32_e32 v225, v225
	v_mul_f32_e32 v218, v88, v218
	v_mul_f32_e32 v219, v89, v219
	v_mul_f32_e32 v220, v90, v220
	v_mul_f32_e32 v221, v91, v221
	v_mul_f32_e32 v222, v80, v222
	v_mul_f32_e32 v223, v81, v223
	v_mul_f32_e32 v224, v82, v224
	v_mul_f32_e32 v225, v83, v225
	v_mul_f32_e32 v92, v92, v166
	v_mul_f32_e32 v93, v93, v166
	v_mul_f32_e32 v94, v94, v166
	v_mul_f32_e32 v95, v95, v166
	v_mul_f32_e32 v84, v84, v166
	v_mul_f32_e32 v85, v85, v166
	v_mul_f32_e32 v86, v86, v166
	v_mul_f32_e32 v87, v87, v166
	v_mul_f32_e32 v92, v92, v218
	v_mul_f32_e32 v93, v93, v219
	v_mul_f32_e32 v94, v94, v220
	v_mul_f32_e32 v95, v95, v221
	v_mul_f32_e32 v84, v84, v222
	v_mul_f32_e32 v85, v85, v223
	v_mul_f32_e32 v86, v86, v224
	v_mul_f32_e32 v87, v87, v225
	v_cvt_pk_bf16_f32 v226, v92, v93
	v_cvt_pk_bf16_f32 v227, v94, v95
	v_cvt_pk_bf16_f32 v228, v84, v85
	v_cvt_pk_bf16_f32 v229, v86, v87
	global_store_dwordx4 v[238:239], v[226:229], off
	v_mul_f32_e32 v72, v72, v174
	v_mul_f32_e32 v73, v73, v174
	v_mul_f32_e32 v74, v74, v174
	v_mul_f32_e32 v75, v75, v174
	v_mul_f32_e32 v64, v64, v174
	v_mul_f32_e32 v65, v65, v174
	v_mul_f32_e32 v66, v66, v174
	v_mul_f32_e32 v67, v67, v174
	v_mul_f32_e32 v218, 0xbfb8aa3b, v72
	v_mul_f32_e32 v219, 0xbfb8aa3b, v73
	v_mul_f32_e32 v220, 0xbfb8aa3b, v74
; __device__ __forceinline__ unsigned cvt_pk_bf16(float lo, float hi) { unsigned r; asm volatile("v_cvt_pk_bf16_f32 %0, %1, %2" : "=v"(r) : "v"(lo), "v"(hi)); return r; }
;     __device__ __forceinline__ void operator()(const f32x4 (&acc)[2][2][4][2], const Unit& u, int wr, int wc, int fr, int fq) const {
;     ...
;                     for (int e = 0; e < 4; ++e) { const float gt = acc[ai][0][m][n][e] * rs, up = acc[ai][1][m][n][e] * rs;
;                         hv[n * 4 + e] = gt * __builtin_amdgcn_rcpf(1.f + __builtin_amdgcn_exp2f(-1.4426950408889634f * gt)) * up; }
;                 u32x4 w; w.x = cvt_pk_bf16(hv[0], hv[1]); w.y = cvt_pk_bf16(hv[2], hv[3]); w.z = cvt_pk_bf16(hv[4], hv[5]); w.w = cvt_pk_bf16(hv[6], hv[7]);
;                 *(u32x4*)(H + (size_t)row * 2816 + col0) = w;
	v_mul_f32_e32 v221, 0xbfb8aa3b, v75
	v_mul_f32_e32 v222, 0xbfb8aa3b, v64
	v_mul_f32_e32 v223, 0xbfb8aa3b, v65
	v_mul_f32_e32 v224, 0xbfb8aa3b, v66
	v_mul_f32_e32 v225, 0xbfb8aa3b, v67
	v_exp_f32_e32 v218, v218
	v_exp_f32_e32 v219, v219
	v_exp_f32_e32 v220, v220
	v_exp_f32_e32 v221, v221
	v_exp_f32_e32 v222, v222
	v_exp_f32_e32 v223, v223
	v_exp_f32_e32 v224, v224
	v_exp_f32_e32 v225, v225
	v_add_f32_e32 v218, 1.0, v218
	v_add_f32_e32 v219, 1.0, v219
	v_add_f32_e32 v220, 1.0, v220
	v_add_f32_e32 v221, 1.0, v221
	v_add_f32_e32 v222, 1.0, v222
	v_add_f32_e32 v223, 1.0, v223
	v_add_f32_e32 v224, 1.0, v224
	v_add_f32_e32 v225, 1.0, v225
	v_rcp_f32_e32 v218, v218
	v_rcp_f32_e32 v219, v219
	v_rcp_f32_e32 v220, v220
	v_rcp_f32_e32 v221, v221
	v_rcp_f32_e32 v222, v222
	v_rcp_f32_e32 v223, v223
	v_rcp_f32_e32 v224, v224
	v_rcp_f32_e32 v225, v225
	v_mul_f32_e32 v218, v72, v218
	v_mul_f32_e32 v219, v73, v219
	v_mul_f32_e32 v220, v74, v220
	v_mul_f32_e32 v221, v75, v221
	v_mul_f32_e32 v222, v64, v222
	v_mul_f32_e32 v223, v65, v223
	v_mul_f32_e32 v224, v66, v224
	v_mul_f32_e32 v225, v67, v225
	v_mul_f32_e32 v76, v76, v174
	v_mul_f32_e32 v77, v77, v174
	v_mul_f32_e32 v78, v78, v174
	v_mul_f32_e32 v79, v79, v174
	v_mul_f32_e32 v68, v68, v174
	v_mul_f32_e32 v69, v69, v174
	v_mul_f32_e32 v70, v70, v174
	v_mul_f32_e32 v71, v71, v174
	v_mul_f32_e32 v76, v76, v218
	v_mul_f32_e32 v77, v77, v219
	v_mul_f32_e32 v78, v78, v220
	v_mul_f32_e32 v79, v79, v221
	v_mul_f32_e32 v68, v68, v222
	v_mul_f32_e32 v69, v69, v223
	v_mul_f32_e32 v70, v70, v224
	v_mul_f32_e32 v71, v71, v225
	v_cvt_pk_bf16_f32 v230, v76, v77
	v_cvt_pk_bf16_f32 v231, v78, v79
	v_cvt_pk_bf16_f32 v232, v68, v69
	v_cvt_pk_bf16_f32 v233, v70, v71
	global_store_dwordx4 v[240:241], v[230:233], off
	v_mul_f32_e32 v56, v56, v178
	v_mul_f32_e32 v57, v57, v178
	v_mul_f32_e32 v58, v58, v178
	v_mul_f32_e32 v59, v59, v178
	v_mul_f32_e32 v48, v48, v178
	v_mul_f32_e32 v49, v49, v178
	v_mul_f32_e32 v50, v50, v178
	v_mul_f32_e32 v51, v51, v178
	v_mul_f32_e32 v218, 0xbfb8aa3b, v56
	v_mul_f32_e32 v219, 0xbfb8aa3b, v57
	v_mul_f32_e32 v220, 0xbfb8aa3b, v58
	v_mul_f32_e32 v221, 0xbfb8aa3b, v59
	v_mul_f32_e32 v222, 0xbfb8aa3b, v48
	v_mul_f32_e32 v223, 0xbfb8aa3b, v49
	v_mul_f32_e32 v224, 0xbfb8aa3b, v50
	v_mul_f32_e32 v225, 0xbfb8aa3b, v51
	v_exp_f32_e32 v218, v218
	v_exp_f32_e32 v219, v219
	v_exp_f32_e32 v220, v220
	v_exp_f32_e32 v221, v221
	v_exp_f32_e32 v222, v222
	v_exp_f32_e32 v223, v223
	v_exp_f32_e32 v224, v224
	v_exp_f32_e32 v225, v225
	v_add_f32_e32 v218, 1.0, v218
	v_add_f32_e32 v219, 1.0, v219
	v_add_f32_e32 v220, 1.0, v220
	v_add_f32_e32 v221, 1.0, v221
	v_add_f32_e32 v222, 1.0, v222
	v_add_f32_e32 v223, 1.0, v223
	v_add_f32_e32 v224, 1.0, v224
	v_add_f32_e32 v225, 1.0, v225
	v_rcp_f32_e32 v218, v218
	v_rcp_f32_e32 v219, v219
	v_rcp_f32_e32 v220, v220
	v_rcp_f32_e32 v221, v221
	v_rcp_f32_e32 v222, v222
	v_rcp_f32_e32 v223, v223
	v_rcp_f32_e32 v224, v224
	v_rcp_f32_e32 v225, v225
	v_mul_f32_e32 v218, v56, v218
	v_mul_f32_e32 v219, v57, v219
	v_mul_f32_e32 v220, v58, v220
	v_mul_f32_e32 v221, v59, v221
	v_mul_f32_e32 v222, v48, v222
	v_mul_f32_e32 v223, v49, v223
	v_mul_f32_e32 v224, v50, v224
	v_mul_f32_e32 v225, v51, v225
	v_mul_f32_e32 v60, v60, v178
	v_mul_f32_e32 v61, v61, v178
	v_mul_f32_e32 v62, v62, v178
	v_mul_f32_e32 v63, v63, v178
	v_mul_f32_e32 v52, v52, v178
	v_mul_f32_e32 v53, v53, v178
	v_mul_f32_e32 v54, v54, v178
	v_mul_f32_e32 v55, v55, v178
	v_mul_f32_e32 v60, v60, v218
	v_mul_f32_e32 v61, v61, v219
	v_mul_f32_e32 v62, v62, v220
	v_mul_f32_e32 v63, v63, v221
	v_mul_f32_e32 v52, v52, v222
	v_mul_f32_e32 v53, v53, v223
	v_mul_f32_e32 v54, v54, v224
	v_mul_f32_e32 v55, v55, v225
	v_cvt_pk_bf16_f32 v226, v60, v61
	v_cvt_pk_bf16_f32 v227, v62, v63
	v_cvt_pk_bf16_f32 v228, v52, v53
	v_cvt_pk_bf16_f32 v229, v54, v55
	v_lshl_add_u64 v[242:243], s[4:5], 3, v[234:235]
	global_store_dwordx4 v[242:243], v[226:229], off
	v_mul_f32_e32 v40, v40, v182
	v_mul_f32_e32 v41, v41, v182
	v_mul_f32_e32 v42, v42, v182
	v_mul_f32_e32 v43, v43, v182
	v_mul_f32_e32 v32, v32, v182
	v_mul_f32_e32 v33, v33, v182
	v_mul_f32_e32 v34, v34, v182
	v_mul_f32_e32 v35, v35, v182
	v_mul_f32_e32 v218, 0xbfb8aa3b, v40
	v_mul_f32_e32 v219, 0xbfb8aa3b, v41
	v_mul_f32_e32 v220, 0xbfb8aa3b, v42
	v_mul_f32_e32 v221, 0xbfb8aa3b, v43
	v_mul_f32_e32 v222, 0xbfb8aa3b, v32
	v_mul_f32_e32 v223, 0xbfb8aa3b, v33
	v_mul_f32_e32 v224, 0xbfb8aa3b, v34
	v_mul_f32_e32 v225, 0xbfb8aa3b, v35
	v_exp_f32_e32 v218, v218
	v_exp_f32_e32 v219, v219
	v_exp_f32_e32 v220, v220
	v_exp_f32_e32 v221, v221
	v_exp_f32_e32 v222, v222
	v_exp_f32_e32 v223, v223
	v_exp_f32_e32 v224, v224
	v_exp_f32_e32 v225, v225
	v_add_f32_e32 v218, 1.0, v218
	v_add_f32_e32 v219, 1.0, v219
	v_add_f32_e32 v220, 1.0, v220
	v_add_f32_e32 v221, 1.0, v221
	v_add_f32_e32 v222, 1.0, v222
	v_add_f32_e32 v223, 1.0, v223
	v_add_f32_e32 v224, 1.0, v224
	v_add_f32_e32 v225, 1.0, v225
	v_rcp_f32_e32 v218, v218
	v_rcp_f32_e32 v219, v219
	v_rcp_f32_e32 v220, v220
	v_rcp_f32_e32 v221, v221
	v_rcp_f32_e32 v222, v222
	v_rcp_f32_e32 v223, v223
	v_rcp_f32_e32 v224, v224
	v_rcp_f32_e32 v225, v225
	v_mul_f32_e32 v218, v40, v218
	v_mul_f32_e32 v219, v41, v219
	v_mul_f32_e32 v220, v42, v220
	v_mul_f32_e32 v221, v43, v221
	v_mul_f32_e32 v222, v32, v222
; __device__ __forceinline__ unsigned cvt_pk_bf16(float lo, float hi) { unsigned r; asm volatile("v_cvt_pk_bf16_f32 %0, %1, %2" : "=v"(r) : "v"(lo), "v"(hi)); return r; }
; #define PG8_BAR __builtin_amdgcn_s_barrier()
;     __device__ __forceinline__ void operator()(const f32x4 (&acc)[2][2][4][2], const Unit& u, int wr, int wc, int fr, int fq) const {
;     ...
;         for (int ai = 0; ai < 2; ++ai)
; #pragma unroll
;             for (int m = 0; m < 4; ++m) {
;                 const int row = row0 + ai * HALF + m * 16;
;                 const float rs = rstd_from(ps, row, 0, 4, 1.f / 1024.f, fq);
;                 float hv[8];
; #pragma unroll
;                 for (int n = 0; n < 2; ++n)
; #pragma unroll
;                     for (int e = 0; e < 4; ++e) { const float gt = acc[ai][0][m][n][e] * rs, up = acc[ai][1][m][n][e] * rs;
;                         hv[n * 4 + e] = gt * __builtin_amdgcn_rcpf(1.f + __builtin_amdgcn_exp2f(-1.4426950408889634f * gt)) * up; }
;                 u32x4 w; w.x = cvt_pk_bf16(hv[0], hv[1]); w.y = cvt_pk_bf16(hv[2], hv[3]); w.z = cvt_pk_bf16(hv[4], hv[5]); w.w = cvt_pk_bf16(hv[6], hv[7]);
;                 *(u32x4*)(H + (size_t)row * 2816 + col0) = w;
; template <class Epi, class Sched, bool ALIGN_EPI = false, bool SP2 = false>
; __device__ __forceinline__ void gemm_phase(PG8_LAS unsigned char* lds, const Gemm g, const Sched& S, const Epi& E) {
;     ...
;         if constexpr (ALIGN_EPI) { if (wr == 0) PG8_BAR; }
;         if constexpr (!Epi::AFTER_DRAIN) { E(acc, cur, wr, wc, fr, fq); S.done(cur); }
;         if (!has_next) break;
; #pragma unroll
;         for (int a = 0; a < 2; ++a)
; #pragma unroll
;             for (int b = 0; b < 2; ++b)
; #pragma unroll
;                 for (int m = 0; m < 4; ++m)
; #pragma unroll
;                     for (int n = 0; n < 2; ++n) acc[a][b][m][n] = (f32x4){0.f, 0.f, 0.f, 0.f};
;         cur = nxt; cA = nA; cB = nB; ++ui;
;         if constexpr (ALIGN_EPI) { if (wr == 1) PG8_BAR; }
	v_mul_f32_e32 v223, v33, v223
	v_mul_f32_e32 v224, v34, v224
	v_mul_f32_e32 v225, v35, v225
	v_mul_f32_e32 v44, v44, v182
	v_mul_f32_e32 v45, v45, v182
	v_mul_f32_e32 v46, v46, v182
	v_mul_f32_e32 v47, v47, v182
	v_mul_f32_e32 v36, v36, v182
	v_mul_f32_e32 v37, v37, v182
	v_mul_f32_e32 v38, v38, v182
	v_mul_f32_e32 v39, v39, v182
	v_mul_f32_e32 v44, v44, v218
	v_mul_f32_e32 v45, v45, v219
	v_mul_f32_e32 v46, v46, v220
	v_mul_f32_e32 v47, v47, v221
	v_mul_f32_e32 v36, v36, v222
	v_mul_f32_e32 v37, v37, v223
	v_mul_f32_e32 v38, v38, v224
	v_mul_f32_e32 v39, v39, v225
	v_cvt_pk_bf16_f32 v230, v44, v45
	v_cvt_pk_bf16_f32 v231, v46, v47
	v_cvt_pk_bf16_f32 v232, v36, v37
	v_cvt_pk_bf16_f32 v233, v38, v39
	v_lshl_add_u64 v[242:243], s[4:5], 3, v[236:237]
	global_store_dwordx4 v[242:243], v[230:233], off
	v_mul_f32_e32 v24, v24, v186
	v_mul_f32_e32 v25, v25, v186
	v_mul_f32_e32 v26, v26, v186
	v_mul_f32_e32 v27, v27, v186
	v_mul_f32_e32 v16, v16, v186
	v_mul_f32_e32 v17, v17, v186
	v_mul_f32_e32 v18, v18, v186
	v_mul_f32_e32 v19, v19, v186
	v_mul_f32_e32 v218, 0xbfb8aa3b, v24
	v_mul_f32_e32 v219, 0xbfb8aa3b, v25
	v_mul_f32_e32 v220, 0xbfb8aa3b, v26
	v_mul_f32_e32 v221, 0xbfb8aa3b, v27
	v_mul_f32_e32 v222, 0xbfb8aa3b, v16
	v_mul_f32_e32 v223, 0xbfb8aa3b, v17
	v_mul_f32_e32 v224, 0xbfb8aa3b, v18
	v_mul_f32_e32 v225, 0xbfb8aa3b, v19
	v_exp_f32_e32 v218, v218
	v_exp_f32_e32 v219, v219
	v_exp_f32_e32 v220, v220
	v_exp_f32_e32 v221, v221
	v_exp_f32_e32 v222, v222
	v_exp_f32_e32 v223, v223
	v_exp_f32_e32 v224, v224
	v_exp_f32_e32 v225, v225
	v_add_f32_e32 v218, 1.0, v218
	v_add_f32_e32 v219, 1.0, v219
	v_add_f32_e32 v220, 1.0, v220
	v_add_f32_e32 v221, 1.0, v221
	v_add_f32_e32 v222, 1.0, v222
	v_add_f32_e32 v223, 1.0, v223
	v_add_f32_e32 v224, 1.0, v224
	v_add_f32_e32 v225, 1.0, v225
	v_rcp_f32_e32 v218, v218
	v_rcp_f32_e32 v219, v219
	v_rcp_f32_e32 v220, v220
	v_rcp_f32_e32 v221, v221
	v_rcp_f32_e32 v222, v222
	v_rcp_f32_e32 v223, v223
	v_rcp_f32_e32 v224, v224
	v_rcp_f32_e32 v225, v225
	v_mul_f32_e32 v218, v24, v218
	v_mul_f32_e32 v219, v25, v219
	v_mul_f32_e32 v220, v26, v220
	v_mul_f32_e32 v221, v27, v221
	v_mul_f32_e32 v222, v16, v222
	v_mul_f32_e32 v223, v17, v223
	v_mul_f32_e32 v224, v18, v224
	v_mul_f32_e32 v225, v19, v225
	v_mul_f32_e32 v28, v28, v186
	v_mul_f32_e32 v29, v29, v186
	v_mul_f32_e32 v30, v30, v186
	v_mul_f32_e32 v31, v31, v186
	v_mul_f32_e32 v20, v20, v186
	v_mul_f32_e32 v21, v21, v186
	v_mul_f32_e32 v22, v22, v186
	v_mul_f32_e32 v23, v23, v186
	v_mul_f32_e32 v28, v28, v218
	v_mul_f32_e32 v29, v29, v219
	v_mul_f32_e32 v30, v30, v220
	v_mul_f32_e32 v31, v31, v221
	v_mul_f32_e32 v20, v20, v222
	v_mul_f32_e32 v21, v21, v223
	v_mul_f32_e32 v22, v22, v224
	v_mul_f32_e32 v23, v23, v225
	v_cvt_pk_bf16_f32 v226, v28, v29
	v_cvt_pk_bf16_f32 v227, v30, v31
	v_cvt_pk_bf16_f32 v228, v20, v21
	v_cvt_pk_bf16_f32 v229, v22, v23
	v_lshl_add_u64 v[242:243], s[4:5], 3, v[238:239]
	global_store_dwordx4 v[242:243], v[226:229], off
	v_mul_f32_e32 v8, v8, v190
	v_mul_f32_e32 v9, v9, v190
	v_mul_f32_e32 v10, v10, v190
	v_mul_f32_e32 v11, v11, v190
	v_mul_f32_e32 v4, v4, v190
	v_mul_f32_e32 v5, v5, v190
	v_mul_f32_e32 v6, v6, v190
	v_mul_f32_e32 v7, v7, v190
	v_mul_f32_e32 v218, 0xbfb8aa3b, v8
	v_mul_f32_e32 v219, 0xbfb8aa3b, v9
	v_mul_f32_e32 v220, 0xbfb8aa3b, v10
	v_mul_f32_e32 v221, 0xbfb8aa3b, v11
	v_mul_f32_e32 v222, 0xbfb8aa3b, v4
	v_mul_f32_e32 v223, 0xbfb8aa3b, v5
	v_mul_f32_e32 v224, 0xbfb8aa3b, v6
	v_mul_f32_e32 v225, 0xbfb8aa3b, v7
	v_exp_f32_e32 v218, v218
	v_exp_f32_e32 v219, v219
	v_exp_f32_e32 v220, v220
	v_exp_f32_e32 v221, v221
	v_exp_f32_e32 v222, v222
	v_exp_f32_e32 v223, v223
	v_exp_f32_e32 v224, v224
	v_exp_f32_e32 v225, v225
	v_add_f32_e32 v218, 1.0, v218
	v_add_f32_e32 v219, 1.0, v219
	v_add_f32_e32 v220, 1.0, v220
	v_add_f32_e32 v221, 1.0, v221
	v_add_f32_e32 v222, 1.0, v222
	v_add_f32_e32 v223, 1.0, v223
	v_add_f32_e32 v224, 1.0, v224
	v_add_f32_e32 v225, 1.0, v225
	v_rcp_f32_e32 v218, v218
	v_rcp_f32_e32 v219, v219
	v_rcp_f32_e32 v220, v220
	v_rcp_f32_e32 v221, v221
	v_rcp_f32_e32 v222, v222
	v_rcp_f32_e32 v223, v223
	v_rcp_f32_e32 v224, v224
	v_rcp_f32_e32 v225, v225
	v_mul_f32_e32 v218, v8, v218
	v_mul_f32_e32 v219, v9, v219
	v_mul_f32_e32 v220, v10, v220
	v_mul_f32_e32 v221, v11, v221
	v_mul_f32_e32 v222, v4, v222
	v_mul_f32_e32 v223, v5, v223
	v_mul_f32_e32 v224, v6, v224
	v_mul_f32_e32 v225, v7, v225
	v_mul_f32_e32 v12, v12, v190
	v_mul_f32_e32 v13, v13, v190
	v_mul_f32_e32 v14, v14, v190
	v_mul_f32_e32 v15, v15, v190
	v_mul_f32_e32 v0, v0, v190
	v_mul_f32_e32 v1, v1, v190
	v_mul_f32_e32 v2, v2, v190
	v_mul_f32_e32 v3, v3, v190
	v_mul_f32_e32 v12, v12, v218
	v_mul_f32_e32 v13, v13, v219
	v_mul_f32_e32 v14, v14, v220
	v_mul_f32_e32 v15, v15, v221
	v_mul_f32_e32 v0, v0, v222
	v_mul_f32_e32 v1, v1, v223
	v_mul_f32_e32 v2, v2, v224
	v_mul_f32_e32 v3, v3, v225
	v_cvt_pk_bf16_f32 v230, v12, v13
	v_cvt_pk_bf16_f32 v231, v14, v15
	v_cvt_pk_bf16_f32 v232, v0, v1
	v_cvt_pk_bf16_f32 v233, v2, v3
	v_lshl_add_u64 v[242:243], s[4:5], 3, v[240:241]
	global_store_dwordx4 v[242:243], v[230:233], off
	s_and_b64 vcc, exec, s[38:39]
	s_mov_b64 s[4:5], -1
	s_cbranch_vccnz .LBB0_1159
	s_andn2_b64 vcc, exec, s[44:45]
	s_cbranch_vccnz .LBB0_1158
	s_barrier
	s_branch .LBB0_1158
